# nt hint on the in-proj / MLP-up / MLP-down epilogue output stores
# speedup vs baseline: 1.0453x; 1.0011x over previous
.LBB0_401:
	s_cmp_gt_i32 s6, 11
	s_cselect_b64 s[30:31], -1, 0
	v_lshl_add_u32 v152, s4, 8, v139
	s_mov_b64 s[4:5], -1
	s_and_b64 vcc, exec, s[30:31]
	s_cbranch_vccz .LBB0_405
	s_and_saveexec_b64 s[4:5], s[16:17]
	s_cbranch_execz .LBB0_404
	v_ashrrev_i32_e32 v153, 31, v152
	v_lshlrev_b64 v[158:159], 6, v[152:153]
	v_lshl_add_u64 v[158:159], v[140:141], 0, v[158:159]
	global_store_dwordx4 v[158:159], v[124:127], off nt
	global_store_dwordx4 v[158:159], v[120:123], off offset:16 nt

.LBB0_405:
	s_andn2_b64 vcc, exec, s[4:5]
	v_lshlrev_b32_e32 v136, 1, v138
	s_cbranch_vccnz .LBB0_407
	s_ashr_i32 s4, s6, 1
	s_mul_hi_i32 s5, s4, 0x3000000
	s_mul_i32 s4, s4, 0x3000000
	s_add_u32 s4, s43, s4
	v_ashrrev_i32_e32 v153, 31, v152
	s_addc_u32 s5, s44, s5
	v_lshlrev_b64 v[158:159], 10, v[152:153]
	v_lshl_add_u64 v[158:159], s[4:5], 0, v[158:159]
	s_lshl_b32 s4, s6, 9
	s_and_b32 s8, s4, 0x200
	v_lshl_add_u64 v[158:159], v[158:159], 0, s[8:9]
	v_lshl_add_u64 v[158:159], v[158:159], 0, v[136:137]
	v_cvt_pk_bf16_f32 v124, v124, v125
	v_cvt_pk_bf16_f32 v125, v126, v127
	v_cvt_pk_bf16_f32 v126, v120, v121
	v_cvt_pk_bf16_f32 v127, v122, v123
	global_store_dwordx4 v[158:159], v[124:127], off nt
	v_cvt_pk_bf16_f32 v116, v116, v117
	v_cvt_pk_bf16_f32 v117, v118, v119
	v_cvt_pk_bf16_f32 v118, v112, v113
	v_cvt_pk_bf16_f32 v119, v114, v115
	global_store_dwordx4 v[158:159], v[116:119], off offset:256 nt

.LBB0_422:
	s_and_saveexec_b64 s[30:31], s[16:17]
	s_cbranch_execz .LBB0_424
	v_ashrrev_i32_e32 v113, 31, v112
	v_lshlrev_b64 v[114:115], 6, v[112:113]
	v_lshl_add_u64 v[114:115], v[140:141], 0, v[114:115]
	global_store_dwordx4 v[114:115], v[108:111], off nt
	global_store_dwordx4 v[114:115], v[104:107], off offset:16 nt

.LBB0_425:
	s_ashr_i32 s8, s6, 1
	s_mul_hi_i32 s19, s8, 0x3000000
	s_mul_i32 s8, s8, 0x3000000
	s_add_u32 s30, s43, s8
	v_ashrrev_i32_e32 v113, 31, v112
	s_addc_u32 s31, s44, s19
	v_lshlrev_b64 v[112:113], 10, v[112:113]
	s_lshl_b32 s8, s6, 9
	v_lshl_add_u64 v[112:113], s[30:31], 0, v[112:113]
	s_and_b32 s8, s8, 0x200
	v_lshl_add_u64 v[112:113], v[112:113], 0, s[8:9]
	v_lshl_add_u64 v[112:113], v[112:113], 0, v[136:137]
	v_cvt_pk_bf16_f32 v108, v108, v109
	v_cvt_pk_bf16_f32 v109, v110, v111
	v_cvt_pk_bf16_f32 v110, v104, v105
	v_cvt_pk_bf16_f32 v111, v106, v107
	global_store_dwordx4 v[112:113], v[108:111], off nt
	v_cvt_pk_bf16_f32 v100, v100, v101
	v_cvt_pk_bf16_f32 v101, v102, v103
	v_cvt_pk_bf16_f32 v102, v96, v97
	v_cvt_pk_bf16_f32 v103, v98, v99
	global_store_dwordx4 v[112:113], v[100:103], off offset:256 nt
	v_or_b32_e32 v96, 32, v152
	s_and_b64 vcc, exec, s[4:5]
	s_mov_b64 s[30:31], -1
	s_cbranch_vccnz .LBB0_410
.LBB0_426:
	s_and_saveexec_b64 s[30:31], s[16:17]
	s_cbranch_execz .LBB0_428
	v_ashrrev_i32_e32 v97, 31, v96
	v_lshlrev_b64 v[98:99], 6, v[96:97]
	v_lshl_add_u64 v[98:99], v[140:141], 0, v[98:99]
	global_store_dwordx4 v[98:99], v[92:95], off nt
	global_store_dwordx4 v[98:99], v[88:91], off offset:16 nt

.LBB0_429:
	s_ashr_i32 s8, s6, 1
	s_mul_hi_i32 s19, s8, 0x3000000
	s_mul_i32 s8, s8, 0x3000000
	s_add_u32 s30, s43, s8
	v_ashrrev_i32_e32 v97, 31, v96
	s_addc_u32 s31, s44, s19
	v_lshlrev_b64 v[96:97], 10, v[96:97]
	s_lshl_b32 s8, s6, 9
	v_lshl_add_u64 v[96:97], s[30:31], 0, v[96:97]
	s_and_b32 s8, s8, 0x200
	v_lshl_add_u64 v[96:97], v[96:97], 0, s[8:9]
	v_lshl_add_u64 v[96:97], v[96:97], 0, v[136:137]
	v_cvt_pk_bf16_f32 v92, v92, v93
	v_cvt_pk_bf16_f32 v93, v94, v95
	v_cvt_pk_bf16_f32 v94, v88, v89
	v_cvt_pk_bf16_f32 v95, v90, v91
	global_store_dwordx4 v[96:97], v[92:95], off nt
	v_cvt_pk_bf16_f32 v84, v84, v85
	v_cvt_pk_bf16_f32 v85, v86, v87
	v_cvt_pk_bf16_f32 v86, v80, v81
	v_cvt_pk_bf16_f32 v87, v82, v83
	global_store_dwordx4 v[96:97], v[84:87], off offset:256 nt
	v_or_b32_e32 v80, 48, v152
	s_and_b64 vcc, exec, s[4:5]
	s_mov_b64 s[30:31], -1
	s_cbranch_vccnz .LBB0_412
.LBB0_430:
	s_and_saveexec_b64 s[30:31], s[16:17]
	s_cbranch_execz .LBB0_432
	v_ashrrev_i32_e32 v81, 31, v80
	v_lshlrev_b64 v[82:83], 6, v[80:81]
	v_lshl_add_u64 v[82:83], v[140:141], 0, v[82:83]
	global_store_dwordx4 v[82:83], v[76:79], off nt
	global_store_dwordx4 v[82:83], v[72:75], off offset:16 nt

.LBB0_433:
	s_ashr_i32 s8, s6, 1
	s_mul_hi_i32 s19, s8, 0x3000000
	s_mul_i32 s8, s8, 0x3000000
	s_add_u32 s30, s43, s8
	v_ashrrev_i32_e32 v81, 31, v80
	s_addc_u32 s31, s44, s19
	v_lshlrev_b64 v[80:81], 10, v[80:81]
	s_lshl_b32 s8, s6, 9
	v_lshl_add_u64 v[80:81], s[30:31], 0, v[80:81]
	s_and_b32 s8, s8, 0x200
	v_lshl_add_u64 v[80:81], v[80:81], 0, s[8:9]
	v_lshl_add_u64 v[80:81], v[80:81], 0, v[136:137]
	v_cvt_pk_bf16_f32 v76, v76, v77
	v_cvt_pk_bf16_f32 v77, v78, v79
	v_cvt_pk_bf16_f32 v78, v72, v73
	v_cvt_pk_bf16_f32 v79, v74, v75
	global_store_dwordx4 v[80:81], v[76:79], off nt
	v_cvt_pk_bf16_f32 v68, v68, v69
	v_cvt_pk_bf16_f32 v69, v70, v71
	v_cvt_pk_bf16_f32 v70, v64, v65
	v_cvt_pk_bf16_f32 v71, v66, v67
	global_store_dwordx4 v[80:81], v[68:71], off offset:256 nt
	v_add_u32_e32 v64, 0x80, v152
	s_and_b64 vcc, exec, s[4:5]
	s_mov_b64 s[30:31], -1
	s_cbranch_vccnz .LBB0_414
.LBB0_434:
	s_and_saveexec_b64 s[30:31], s[16:17]
	s_cbranch_execz .LBB0_436
	v_ashrrev_i32_e32 v65, 31, v64
	v_lshlrev_b64 v[66:67], 6, v[64:65]
	v_lshl_add_u64 v[66:67], v[140:141], 0, v[66:67]
	global_store_dwordx4 v[66:67], v[60:63], off nt
	global_store_dwordx4 v[66:67], v[56:59], off offset:16 nt

.LBB0_437:
	s_ashr_i32 s8, s6, 1
	s_mul_hi_i32 s19, s8, 0x3000000
	s_mul_i32 s8, s8, 0x3000000
	s_add_u32 s30, s43, s8
	v_ashrrev_i32_e32 v65, 31, v64
	s_addc_u32 s31, s44, s19
	v_lshlrev_b64 v[64:65], 10, v[64:65]
	s_lshl_b32 s8, s6, 9
	v_lshl_add_u64 v[64:65], s[30:31], 0, v[64:65]
	s_and_b32 s8, s8, 0x200
	v_lshl_add_u64 v[64:65], v[64:65], 0, s[8:9]
	v_lshl_add_u64 v[64:65], v[64:65], 0, v[136:137]
	v_cvt_pk_bf16_f32 v60, v60, v61
	v_cvt_pk_bf16_f32 v61, v62, v63
	v_cvt_pk_bf16_f32 v62, v56, v57
	v_cvt_pk_bf16_f32 v63, v58, v59
	global_store_dwordx4 v[64:65], v[60:63], off nt
	v_cvt_pk_bf16_f32 v52, v52, v53
	v_cvt_pk_bf16_f32 v53, v54, v55
	v_cvt_pk_bf16_f32 v54, v48, v49
	v_cvt_pk_bf16_f32 v55, v50, v51
	global_store_dwordx4 v[64:65], v[52:55], off offset:256 nt
	v_add_u32_e32 v48, 0x90, v152
	s_and_b64 vcc, exec, s[4:5]
	s_mov_b64 s[30:31], -1
	s_cbranch_vccnz .LBB0_416
.LBB0_438:
	s_and_saveexec_b64 s[30:31], s[16:17]
	s_cbranch_execz .LBB0_440
	v_ashrrev_i32_e32 v49, 31, v48
	v_lshlrev_b64 v[50:51], 6, v[48:49]
	v_lshl_add_u64 v[50:51], v[140:141], 0, v[50:51]
	global_store_dwordx4 v[50:51], v[44:47], off nt
	global_store_dwordx4 v[50:51], v[40:43], off offset:16 nt

.LBB0_441:
	s_ashr_i32 s8, s6, 1
	s_mul_hi_i32 s19, s8, 0x3000000
	s_mul_i32 s8, s8, 0x3000000
	s_add_u32 s30, s43, s8
	v_ashrrev_i32_e32 v49, 31, v48
	s_addc_u32 s31, s44, s19
	v_lshlrev_b64 v[48:49], 10, v[48:49]
	s_lshl_b32 s8, s6, 9
	v_lshl_add_u64 v[48:49], s[30:31], 0, v[48:49]
	s_and_b32 s8, s8, 0x200
	v_lshl_add_u64 v[48:49], v[48:49], 0, s[8:9]
	v_lshl_add_u64 v[48:49], v[48:49], 0, v[136:137]
	v_cvt_pk_bf16_f32 v44, v44, v45
	v_cvt_pk_bf16_f32 v45, v46, v47
	v_cvt_pk_bf16_f32 v46, v40, v41
	v_cvt_pk_bf16_f32 v47, v42, v43
	global_store_dwordx4 v[48:49], v[44:47], off nt
	v_cvt_pk_bf16_f32 v36, v36, v37
	v_cvt_pk_bf16_f32 v37, v38, v39
	v_cvt_pk_bf16_f32 v38, v32, v33
	v_cvt_pk_bf16_f32 v39, v34, v35
	global_store_dwordx4 v[48:49], v[36:39], off offset:256 nt
	v_add_u32_e32 v32, 0xa0, v152
	s_and_b64 vcc, exec, s[4:5]
	s_mov_b64 s[30:31], -1
	s_cbranch_vccnz .LBB0_418
.LBB0_442:
	s_and_saveexec_b64 s[30:31], s[16:17]
	s_cbranch_execz .LBB0_444
	v_ashrrev_i32_e32 v33, 31, v32
	v_lshlrev_b64 v[34:35], 6, v[32:33]
	v_lshl_add_u64 v[34:35], v[140:141], 0, v[34:35]
	global_store_dwordx4 v[34:35], v[28:31], off nt
	global_store_dwordx4 v[34:35], v[24:27], off offset:16 nt

.LBB0_445:
	s_ashr_i32 s8, s6, 1
	s_mul_hi_i32 s19, s8, 0x3000000
	s_mul_i32 s8, s8, 0x3000000
	s_add_u32 s30, s43, s8
	v_ashrrev_i32_e32 v33, 31, v32
	s_addc_u32 s31, s44, s19
	v_lshlrev_b64 v[32:33], 10, v[32:33]
	s_lshl_b32 s8, s6, 9
	v_lshl_add_u64 v[32:33], s[30:31], 0, v[32:33]
	s_and_b32 s8, s8, 0x200
	v_lshl_add_u64 v[32:33], v[32:33], 0, s[8:9]
	v_lshl_add_u64 v[32:33], v[32:33], 0, v[136:137]
	v_cvt_pk_bf16_f32 v28, v28, v29
	v_cvt_pk_bf16_f32 v29, v30, v31
	v_cvt_pk_bf16_f32 v30, v24, v25
	v_cvt_pk_bf16_f32 v31, v26, v27
	global_store_dwordx4 v[32:33], v[28:31], off nt
	v_cvt_pk_bf16_f32 v20, v20, v21
	v_cvt_pk_bf16_f32 v21, v22, v23
	v_cvt_pk_bf16_f32 v22, v16, v17
	v_cvt_pk_bf16_f32 v23, v18, v19
	global_store_dwordx4 v[32:33], v[20:23], off offset:256 nt
	v_add_u32_e32 v16, 0xb0, v152
	s_and_b64 vcc, exec, s[4:5]
	s_mov_b64 s[4:5], -1
	s_cbranch_vccnz .LBB0_420
.LBB0_446:
	s_and_saveexec_b64 s[4:5], s[16:17]
	s_cbranch_execz .LBB0_448
	v_ashrrev_i32_e32 v17, 31, v16
	v_lshlrev_b64 v[18:19], 6, v[16:17]
	v_lshl_add_u64 v[18:19], v[140:141], 0, v[18:19]
	global_store_dwordx4 v[18:19], v[12:15], off nt
	global_store_dwordx4 v[18:19], v[8:11], off offset:16 nt

.LBB0_449:
	s_ashr_i32 s4, s6, 1
	s_mul_hi_i32 s5, s4, 0x3000000
	s_mul_i32 s4, s4, 0x3000000
	s_add_u32 s4, s43, s4
	v_ashrrev_i32_e32 v17, 31, v16
	s_addc_u32 s5, s44, s5
	v_lshlrev_b64 v[16:17], 10, v[16:17]
	v_lshl_add_u64 v[16:17], s[4:5], 0, v[16:17]
	s_lshl_b32 s4, s6, 9
	s_and_b32 s8, s4, 0x200
	v_lshl_add_u64 v[16:17], v[16:17], 0, s[8:9]
	v_lshl_add_u64 v[16:17], v[16:17], 0, v[136:137]
	v_cvt_pk_bf16_f32 v12, v12, v13
	v_cvt_pk_bf16_f32 v13, v14, v15
	v_cvt_pk_bf16_f32 v14, v8, v9
	v_cvt_pk_bf16_f32 v15, v10, v11
	global_store_dwordx4 v[16:17], v[12:15], off nt
	v_cvt_pk_bf16_f32 v4, v4, v5
	v_cvt_pk_bf16_f32 v5, v6, v7
	v_cvt_pk_bf16_f32 v6, v0, v1
	v_cvt_pk_bf16_f32 v7, v2, v3
	global_store_dwordx4 v[16:17], v[4:7], off offset:256 nt
	s_andn2_b64 vcc, exec, s[0:1]
	s_mov_b64 s[0:1], -1
	s_cbranch_vccnz .LBB0_394

.LBB0_2112:
	v_lshl_add_u32 v160, s2, 8, v151
	v_ashrrev_i32_e32 v161, 31, v160
	v_lshl_add_u64 v[168:169], v[160:161], 2, s[12:13]
	global_load_dword v150, v[168:169], off
	v_or_b32_e32 v152, 16, v160
	v_ashrrev_i32_e32 v153, 31, v152
	v_or_b32_e32 v148, 32, v160
	v_or_b32_e32 v146, 48, v160
	v_lshl_add_u64 v[170:171], v[152:153], 2, s[12:13]
	v_ashrrev_i32_e32 v149, 31, v148
	v_ashrrev_i32_e32 v147, 31, v146
	v_lshl_add_u64 v[172:173], v[148:149], 2, s[12:13]
	v_lshl_add_u64 v[174:175], v[146:147], 2, s[12:13]
	global_load_dword v154, v[170:171], off
	global_load_dword v156, v[172:173], off
	global_load_dword v158, v[174:175], off
	global_load_dword v162, v[168:169], off offset:512
	s_nop 0
	global_load_dword v170, v[168:169], off offset:576
	global_load_dword v171, v[168:169], off offset:640
	s_nop 0
	global_load_dword v169, v[168:169], off offset:704
	s_lshl_b32 s36, s3, 8
	v_readlane_b32 s60, v244, 0
	v_readlane_b32 s64, v244, 4
	v_readlane_b32 s65, v244, 5
	v_readlane_b32 s66, v244, 6
	v_readlane_b32 s67, v244, 7
	s_ashr_i32 s37, s36, 31
	v_readlane_b32 s61, v244, 1
	v_readlane_b32 s62, v244, 2
	v_readlane_b32 s63, v244, 3
	s_waitcnt vmcnt(0)
	v_fmamk_f32 v150, v150, 0x3a800000, v165
	v_mul_f32_e32 v164, 0x4f800000, v150
	v_cmp_gt_f32_e32 vcc, s54, v150
	v_fmamk_f32 v154, v154, 0x3a800000, v165
	s_nop 0
	v_cndmask_b32_e32 v150, v150, v164, vcc
	v_fmamk_f32 v156, v156, 0x3a800000, v165
	v_mul_f32_e32 v164, 0x4f800000, v154
	v_sqrt_f32_e32 v168, v150
	v_cmp_gt_f32_e64 s[2:3], s54, v154
	v_mul_f32_e32 v166, 0x4f800000, v156
	v_cmp_gt_f32_e64 s[4:5], s54, v156
	v_cndmask_b32_e64 v154, v154, v164, s[2:3]
	v_sqrt_f32_e32 v164, v154
	v_cndmask_b32_e64 v156, v156, v166, s[4:5]
	v_sqrt_f32_e32 v166, v156
	v_add_u32_e32 v173, -1, v168
	v_add_u32_e32 v174, 1, v168
	v_fma_f32 v175, -v173, v168, v150
	v_fma_f32 v176, -v174, v168, v150
	v_add_u32_e32 v177, -1, v164
	v_cmp_ge_f32_e64 s[6:7], 0, v175
	v_add_u32_e32 v179, -1, v166
	v_add_u32_e32 v178, 1, v164
	v_cndmask_b32_e64 v168, v168, v173, s[6:7]
	v_fma_f32 v173, -v177, v164, v154
	v_cmp_lt_f32_e64 s[6:7], 0, v176
	v_fma_f32 v181, -v179, v166, v156
	v_add_u32_e32 v180, 1, v166
	v_cndmask_b32_e64 v168, v168, v174, s[6:7]
	v_cmp_ge_f32_e64 s[6:7], 0, v173
	v_fma_f32 v175, -v178, v164, v154
	v_fma_f32 v183, -v180, v166, v156
	v_cndmask_b32_e64 v164, v164, v177, s[6:7]
	v_cmp_ge_f32_e64 s[6:7], 0, v181
	v_mul_f32_e32 v173, 0x37800000, v168
	v_cndmask_b32_e32 v168, v168, v173, vcc
	v_cndmask_b32_e64 v166, v166, v179, s[6:7]
	v_cmp_lt_f32_e64 s[6:7], 0, v175
	v_cmp_class_f32_e32 vcc, v150, v167
	v_fmamk_f32 v158, v158, 0x3a800000, v165
	v_cndmask_b32_e64 v164, v164, v178, s[6:7]
	v_cmp_lt_f32_e64 s[6:7], 0, v183
	v_mul_f32_e32 v173, 0x37800000, v164
	v_cndmask_b32_e32 v150, v168, v150, vcc
	v_cndmask_b32_e64 v166, v166, v180, s[6:7]
	v_cndmask_b32_e64 v164, v164, v173, s[2:3]
	v_div_scale_f32 v168, s[2:3], v150, v150, 1.0
	v_mul_f32_e32 v174, 0x37800000, v166
	v_cmp_class_f32_e64 s[2:3], v154, v167
	v_cndmask_b32_e64 v166, v166, v174, s[4:5]
	v_div_scale_f32 v173, vcc, 1.0, v150, 1.0
	v_cndmask_b32_e64 v154, v164, v154, s[2:3]
	v_cmp_class_f32_e64 s[2:3], v156, v167
	v_rcp_f32_e32 v164, v168
	v_mul_f32_e32 v172, 0x4f800000, v158
	v_cndmask_b32_e64 v156, v166, v156, s[2:3]
	v_div_scale_f32 v166, s[2:3], v154, v154, 1.0
	v_div_scale_f32 v175, s[4:5], v156, v156, 1.0
	v_rcp_f32_e32 v177, v166
	v_rcp_f32_e32 v178, v175
	v_fma_f32 v179, -v168, v164, 1.0
	v_fmac_f32_e32 v164, v179, v164
	v_fma_f32 v179, -v166, v177, 1.0
	v_div_scale_f32 v174, s[2:3], 1.0, v154, 1.0
	v_fma_f32 v180, -v175, v178, 1.0
	v_mul_f32_e32 v181, v173, v164
	v_fmac_f32_e32 v177, v179, v177
	v_fmac_f32_e32 v178, v180, v178
	v_fma_f32 v179, -v168, v181, v173
	v_mul_f32_e32 v180, v174, v177
	v_fmac_f32_e32 v181, v179, v164
	v_fma_f32 v179, -v166, v180, v174
	v_fma_f32 v168, -v168, v181, v173
	v_fmac_f32_e32 v180, v179, v177
	v_div_fmas_f32 v164, v168, v164, v181
	v_fma_f32 v166, -v166, v180, v174
	s_mov_b64 vcc, s[2:3]
	v_div_fixup_f32 v168, v164, v150, 1.0
	v_div_fmas_f32 v150, v166, v177, v180
	v_cmp_gt_f32_e32 vcc, s54, v158
	v_div_fixup_f32 v166, v150, v154, 1.0
	v_div_scale_f32 v176, s[4:5], 1.0, v156, 1.0
	v_cndmask_b32_e32 v150, v158, v172, vcc
	v_sqrt_f32_e32 v154, v150
	v_mul_f32_e32 v183, v176, v178
	v_fma_f32 v158, -v175, v183, v176
	v_fmac_f32_e32 v183, v158, v178
	v_add_u32_e32 v164, -1, v154
	v_fma_f32 v172, -v164, v154, v150
	v_cmp_ge_f32_e64 s[2:3], 0, v172
	v_add_u32_e32 v172, 1, v154
	v_fma_f32 v158, -v175, v183, v176
	v_cndmask_b32_e64 v164, v154, v164, s[2:3]
	v_fma_f32 v154, -v172, v154, v150
	v_cmp_lt_f32_e64 s[2:3], 0, v154
	v_fmamk_f32 v162, v162, 0x3a800000, v165
	v_mul_f32_e32 v173, 0x4f800000, v162
	v_cndmask_b32_e64 v154, v164, v172, s[2:3]
	v_mul_f32_e32 v164, 0x37800000, v154
	v_cndmask_b32_e32 v154, v154, v164, vcc
	v_cmp_class_f32_e32 vcc, v150, v167
	v_fmamk_f32 v169, v169, 0x3a800000, v165
	v_pk_mul_f32 v[106:107], v[106:107], v[166:167] op_sel_hi:[1,0]
	v_cndmask_b32_e32 v150, v154, v150, vcc
	v_div_scale_f32 v154, s[2:3], v150, v150, 1.0
	v_rcp_f32_e32 v172, v154
	s_mov_b64 vcc, s[4:5]
	v_div_fmas_f32 v158, v158, v178, v183
	v_cmp_gt_f32_e64 s[2:3], s54, v162
	v_div_fixup_f32 v164, v158, v156, 1.0
	v_fma_f32 v156, -v154, v172, 1.0
	v_cndmask_b32_e64 v162, v162, v173, s[2:3]
	v_fmac_f32_e32 v172, v156, v172
	v_div_scale_f32 v156, vcc, 1.0, v150, 1.0
	v_sqrt_f32_e32 v173, v162
	v_mul_f32_e32 v158, v156, v172
	v_fma_f32 v174, -v154, v158, v156
	v_fmac_f32_e32 v158, v174, v172
	v_fma_f32 v154, -v154, v158, v156
	v_add_u32_e32 v156, -1, v173
	v_fma_f32 v174, -v156, v173, v162
	v_cmp_ge_f32_e64 s[4:5], 0, v174
	v_add_u32_e32 v174, 1, v173
	v_div_fmas_f32 v154, v154, v172, v158
	v_cndmask_b32_e64 v156, v173, v156, s[4:5]
	v_fma_f32 v173, -v174, v173, v162
	v_cmp_lt_f32_e64 s[4:5], 0, v173
	v_fmamk_f32 v158, v170, 0x3a800000, v165
	v_mul_f32_e32 v170, 0x4f800000, v158
	v_cndmask_b32_e64 v156, v156, v174, s[4:5]
	v_mul_f32_e32 v173, 0x37800000, v156
	v_cndmask_b32_e64 v156, v156, v173, s[2:3]
	v_cmp_class_f32_e64 s[2:3], v162, v167
	v_pk_mul_f32 v[104:105], v[104:105], v[166:167] op_sel_hi:[1,0]
	v_pk_mul_f32 v[110:111], v[110:111], v[166:167] op_sel_hi:[1,0]
	v_cndmask_b32_e64 v156, v156, v162, s[2:3]
	v_div_scale_f32 v173, s[2:3], v156, v156, 1.0
	v_rcp_f32_e32 v174, v173
	v_cmp_gt_f32_e64 s[2:3], s54, v158
	v_div_fixup_f32 v162, v154, v150, 1.0
	v_pk_mul_f32 v[108:109], v[108:109], v[166:167] op_sel_hi:[1,0]
	v_cndmask_b32_e64 v158, v158, v170, s[2:3]
	v_fma_f32 v150, -v173, v174, 1.0
	v_sqrt_f32_e32 v170, v158
	v_fmac_f32_e32 v174, v150, v174
	v_div_scale_f32 v150, vcc, 1.0, v156, 1.0
	v_mul_f32_e32 v154, v150, v174
	v_fma_f32 v172, -v173, v154, v150
	v_fmac_f32_e32 v154, v172, v174
	v_add_u32_e32 v172, -1, v170
	v_fma_f32 v150, -v173, v154, v150
	v_fma_f32 v173, -v172, v170, v158
	v_cmp_ge_f32_e64 s[4:5], 0, v173
	v_add_u32_e32 v173, 1, v170
	v_div_fmas_f32 v150, v150, v174, v154
	v_cndmask_b32_e64 v172, v170, v172, s[4:5]
	v_fma_f32 v170, -v173, v170, v158
	v_cmp_lt_f32_e64 s[4:5], 0, v170
	v_max_f32_e32 v104, 0, v104
	v_max_f32_e32 v105, 0, v105
	v_cndmask_b32_e64 v170, v172, v173, s[4:5]
	v_mul_f32_e32 v172, 0x37800000, v170
	v_cndmask_b32_e64 v170, v170, v172, s[2:3]
	v_cmp_class_f32_e64 s[2:3], v158, v167
	v_max_f32_e32 v106, 0, v106
	v_max_f32_e32 v108, 0, v108
	v_cndmask_b32_e64 v170, v170, v158, s[2:3]
	v_div_scale_f32 v172, s[2:3], v170, v170, 1.0
	v_rcp_f32_e32 v173, v172
	v_div_fixup_f32 v158, v150, v156, 1.0
	v_fmamk_f32 v156, v171, 0x3a800000, v165
	v_mul_f32_e32 v171, 0x4f800000, v156
	v_cmp_gt_f32_e64 s[2:3], s54, v156
	v_fma_f32 v150, -v172, v173, 1.0
	v_fmac_f32_e32 v173, v150, v173
	v_cndmask_b32_e64 v156, v156, v171, s[2:3]
	v_div_scale_f32 v150, vcc, 1.0, v170, 1.0
	v_sqrt_f32_e32 v171, v156
	v_mul_f32_e32 v154, v150, v173
	v_fma_f32 v174, -v172, v154, v150
	v_fmac_f32_e32 v154, v174, v173
	v_fma_f32 v150, -v172, v154, v150
	v_add_u32_e32 v172, -1, v171
	v_fma_f32 v174, -v172, v171, v156
	v_cmp_ge_f32_e64 s[4:5], 0, v174
	v_add_u32_e32 v174, 1, v171
	v_div_fmas_f32 v150, v150, v173, v154
	v_cndmask_b32_e64 v172, v171, v172, s[4:5]
	v_fma_f32 v171, -v174, v171, v156
	v_cmp_lt_f32_e64 s[4:5], 0, v171
	v_mul_f32_e32 v108, v108, v108
	v_max_f32_e32 v107, 0, v107
	v_cndmask_b32_e64 v171, v172, v174, s[4:5]
	v_mul_f32_e32 v172, 0x37800000, v171
	v_cndmask_b32_e64 v171, v171, v172, s[2:3]
	v_cmp_class_f32_e64 s[2:3], v156, v167
	v_pk_mul_f32 v[96:97], v[96:97], v[166:167] op_sel_hi:[1,0]
	v_mul_f32_e32 v107, v107, v107
	v_cndmask_b32_e64 v171, v171, v156, s[2:3]
	v_div_scale_f32 v172, s[2:3], v171, v171, 1.0
	v_rcp_f32_e32 v174, v172
	v_div_fixup_f32 v156, v150, v170, 1.0
	v_mul_f32_e32 v170, 0x4f800000, v169
	v_cmp_gt_f32_e64 s[2:3], s54, v169
	v_fma_f32 v150, -v172, v174, 1.0
	v_fmac_f32_e32 v174, v150, v174
	v_cndmask_b32_e64 v169, v169, v170, s[2:3]
	v_div_scale_f32 v150, vcc, 1.0, v171, 1.0
	v_sqrt_f32_e32 v170, v169
	v_mul_f32_e32 v154, v150, v174
	v_fma_f32 v173, -v172, v154, v150
	v_fmac_f32_e32 v154, v173, v174
	v_fma_f32 v150, -v172, v154, v150
	v_add_u32_e32 v172, -1, v170
	v_fma_f32 v173, -v172, v170, v169
	v_cmp_ge_f32_e64 s[4:5], 0, v173
	v_add_u32_e32 v173, 1, v170
	v_div_fmas_f32 v150, v150, v174, v154
	v_cndmask_b32_e64 v172, v170, v172, s[4:5]
	v_fma_f32 v170, -v173, v170, v169
	v_cmp_lt_f32_e64 s[4:5], 0, v170
	v_div_fixup_f32 v154, v150, v171, 1.0
	v_pk_mul_f32 v[100:101], v[100:101], v[166:167] op_sel_hi:[1,0]
	v_cndmask_b32_e64 v170, v172, v173, s[4:5]
	v_mul_f32_e32 v172, 0x37800000, v170
	v_cndmask_b32_e64 v170, v170, v172, s[2:3]
	v_cmp_class_f32_e64 s[2:3], v169, v167
	s_mov_b64 s[4:5], s[64:65]
	s_mov_b64 s[6:7], s[66:67]
	v_cndmask_b32_e64 v169, v170, v169, s[2:3]
	v_div_scale_f32 v170, s[2:3], v169, v169, 1.0
	v_rcp_f32_e32 v172, v170
	v_pk_mul_f32 v[124:125], v[124:125], v[168:169] op_sel_hi:[1,0]
	v_pk_mul_f32 v[122:123], v[122:123], v[168:169] op_sel_hi:[1,0]
	v_pk_mul_f32 v[120:121], v[120:121], v[168:169] op_sel_hi:[1,0]
	v_fma_f32 v150, -v170, v172, 1.0
	v_fmac_f32_e32 v172, v150, v172
	v_div_scale_f32 v150, vcc, 1.0, v169, 1.0
	v_mul_f32_e32 v171, v150, v172
	v_fma_f32 v173, -v170, v171, v150
	v_fmac_f32_e32 v171, v173, v172
	v_fma_f32 v150, -v170, v171, v150
	v_div_fmas_f32 v150, v150, v172, v171
	v_pk_mul_f32 v[126:127], v[126:127], v[168:169] op_sel_hi:[1,0]
	v_max_f32_e32 v124, 0, v124
	v_max_f32_e32 v120, 0, v120
	v_max_f32_e32 v121, 0, v121
	v_max_f32_e32 v122, 0, v122
	v_div_fixup_f32 v150, v150, v169, 1.0
	v_mul_f32_e32 v124, v124, v124
	v_mul_f32_e32 v120, v120, v120
	v_max_f32_e32 v125, 0, v125
	v_mul_f32_e32 v121, v121, v121
	v_max_f32_e32 v126, 0, v126
	v_mul_f32_e32 v169, v122, v122
	v_max_f32_e32 v122, 0, v127
	v_max_f32_e32 v123, 0, v123
	v_mul_f32_e32 v125, v125, v125
	v_mul_f32_e32 v126, v126, v126
	v_mul_f32_e32 v127, v122, v122
	v_mul_f32_e32 v170, v123, v123
	v_cvt_pk_bf16_f32 v122, v124, v125
	v_cvt_pk_bf16_f32 v123, v126, v127
	v_cvt_pk_bf16_f32 v124, v120, v121
	v_lshlrev_b64 v[120:121], 13, v[160:161]
	v_lshl_add_u64 v[120:121], s[6:7], 0, v[120:121]
	s_lshl_b64 s[2:3], s[36:37], 1
	v_lshl_add_u64 v[120:121], v[120:121], 0, s[2:3]
	v_pk_mul_f32 v[112:113], v[112:113], v[168:169] op_sel_hi:[1,0]
	v_lshl_add_u64 v[120:121], v[120:121], 0, v[136:137]
	v_pk_mul_f32 v[116:117], v[116:117], v[168:169] op_sel_hi:[1,0]
	v_pk_mul_f32 v[114:115], v[114:115], v[168:169] op_sel_hi:[1,0]
	v_max_f32_e32 v112, 0, v112
	v_cvt_pk_bf16_f32 v125, v169, v170
	global_store_dwordx4 v[120:121], v[122:125], off nt
	v_pk_mul_f32 v[118:119], v[118:119], v[168:169] op_sel_hi:[1,0]
	v_max_f32_e32 v113, 0, v113
	v_mul_f32_e32 v122, v112, v112
	v_max_f32_e32 v112, 0, v117
	v_max_f32_e32 v114, 0, v114
	v_max_f32_e32 v116, 0, v116
	v_mul_f32_e32 v112, v112, v112
	v_mul_f32_e32 v117, v113, v113
	v_max_f32_e32 v113, 0, v118
	v_mul_f32_e32 v118, v114, v114
	v_max_f32_e32 v114, 0, v119
	v_max_f32_e32 v115, 0, v115
	v_mul_f32_e32 v116, v116, v116
	v_mul_f32_e32 v113, v113, v113
	v_mul_f32_e32 v114, v114, v114
	v_mul_f32_e32 v115, v115, v115
	v_cvt_pk_bf16_f32 v112, v116, v112
	v_cvt_pk_bf16_f32 v113, v113, v114
	v_cvt_pk_bf16_f32 v114, v122, v117
	v_cvt_pk_bf16_f32 v115, v118, v115
	global_store_dwordx4 v[120:121], v[112:115], off offset:256 nt
	v_pk_mul_f32 v[98:99], v[98:99], v[166:167] op_sel_hi:[1,0]
	v_max_f32_e32 v96, 0, v96
	v_mul_f32_e32 v112, v104, v104
	v_max_f32_e32 v104, 0, v109
	v_mul_f32_e32 v109, v105, v105
	v_max_f32_e32 v105, 0, v110
	v_mul_f32_e32 v110, v106, v106
	v_max_f32_e32 v106, 0, v111
	v_mul_f32_e32 v104, v104, v104
	v_mul_f32_e32 v105, v105, v105
	v_mul_f32_e32 v106, v106, v106
	v_cvt_pk_bf16_f32 v104, v108, v104
	v_cvt_pk_bf16_f32 v105, v105, v106
	v_cvt_pk_bf16_f32 v106, v112, v109
	v_lshlrev_b64 v[108:109], 13, v[152:153]
	v_lshl_add_u64 v[108:109], s[6:7], 0, v[108:109]
	v_lshl_add_u64 v[108:109], v[108:109], 0, s[2:3]
	v_lshl_add_u64 v[108:109], v[108:109], 0, v[136:137]
	v_cvt_pk_bf16_f32 v107, v110, v107
	global_store_dwordx4 v[108:109], v[104:107], off nt
	v_pk_mul_f32 v[102:103], v[102:103], v[166:167] op_sel_hi:[1,0]
	v_max_f32_e32 v97, 0, v97
	v_mul_f32_e32 v104, v96, v96
	v_max_f32_e32 v96, 0, v101
	v_max_f32_e32 v98, 0, v98
	v_max_f32_e32 v100, 0, v100
	v_mul_f32_e32 v96, v96, v96
	v_mul_f32_e32 v101, v97, v97
	v_max_f32_e32 v97, 0, v102
	v_mul_f32_e32 v102, v98, v98
	v_max_f32_e32 v98, 0, v103
	v_max_f32_e32 v99, 0, v99
	v_pk_mul_f32 v[90:91], v[90:91], v[164:165] op_sel_hi:[1,0]
	v_pk_mul_f32 v[88:89], v[88:89], v[164:165] op_sel_hi:[1,0]
	v_mul_f32_e32 v100, v100, v100
	v_mul_f32_e32 v97, v97, v97
	v_mul_f32_e32 v98, v98, v98
	v_mul_f32_e32 v99, v99, v99
	v_cvt_pk_bf16_f32 v96, v100, v96
	v_pk_mul_f32 v[94:95], v[94:95], v[164:165] op_sel_hi:[1,0]
	v_pk_mul_f32 v[92:93], v[92:93], v[164:165] op_sel_hi:[1,0]
	v_max_f32_e32 v88, 0, v88
	v_max_f32_e32 v89, 0, v89
	v_max_f32_e32 v90, 0, v90
	v_cvt_pk_bf16_f32 v97, v97, v98
	v_cvt_pk_bf16_f32 v98, v104, v101
	v_cvt_pk_bf16_f32 v99, v102, v99
	global_store_dwordx4 v[108:109], v[96:99], off offset:256 nt
	v_max_f32_e32 v92, 0, v92
	v_mul_f32_e32 v92, v92, v92
	v_mul_f32_e32 v96, v88, v88
	v_max_f32_e32 v88, 0, v93
	v_mul_f32_e32 v93, v89, v89
	v_max_f32_e32 v89, 0, v94
	v_mul_f32_e32 v94, v90, v90
	v_max_f32_e32 v90, 0, v95
	v_mul_f32_e32 v88, v88, v88
	v_mul_f32_e32 v89, v89, v89
	v_mul_f32_e32 v90, v90, v90
	v_cvt_pk_bf16_f32 v88, v92, v88
	v_cvt_pk_bf16_f32 v89, v89, v90
	v_cvt_pk_bf16_f32 v90, v96, v93
	v_lshlrev_b64 v[92:93], 13, v[148:149]
	v_lshl_add_u64 v[92:93], s[6:7], 0, v[92:93]
	v_max_f32_e32 v91, 0, v91
	v_lshl_add_u64 v[92:93], v[92:93], 0, s[2:3]
	v_pk_mul_f32 v[80:81], v[80:81], v[164:165] op_sel_hi:[1,0]
	v_mul_f32_e32 v91, v91, v91
	v_lshl_add_u64 v[92:93], v[92:93], 0, v[136:137]
	v_pk_mul_f32 v[84:85], v[84:85], v[164:165] op_sel_hi:[1,0]
	v_pk_mul_f32 v[82:83], v[82:83], v[164:165] op_sel_hi:[1,0]
	v_max_f32_e32 v80, 0, v80
	v_cvt_pk_bf16_f32 v91, v94, v91
	global_store_dwordx4 v[92:93], v[88:91], off nt
	v_pk_mul_f32 v[86:87], v[86:87], v[164:165] op_sel_hi:[1,0]
	v_max_f32_e32 v81, 0, v81
	v_mul_f32_e32 v88, v80, v80
	v_max_f32_e32 v80, 0, v85
	v_max_f32_e32 v82, 0, v82
	v_max_f32_e32 v84, 0, v84
	v_mul_f32_e32 v80, v80, v80
	v_mul_f32_e32 v85, v81, v81
	v_max_f32_e32 v81, 0, v86
	v_mul_f32_e32 v86, v82, v82
	v_max_f32_e32 v82, 0, v87
	v_max_f32_e32 v83, 0, v83
	v_pk_mul_f32 v[74:75], v[74:75], v[162:163] op_sel_hi:[1,0]
	v_pk_mul_f32 v[72:73], v[72:73], v[162:163] op_sel_hi:[1,0]
	v_mul_f32_e32 v84, v84, v84
	v_mul_f32_e32 v81, v81, v81
	v_mul_f32_e32 v82, v82, v82
	v_mul_f32_e32 v83, v83, v83
	v_cvt_pk_bf16_f32 v80, v84, v80
	v_pk_mul_f32 v[78:79], v[78:79], v[162:163] op_sel_hi:[1,0]
	v_pk_mul_f32 v[76:77], v[76:77], v[162:163] op_sel_hi:[1,0]
	v_max_f32_e32 v72, 0, v72
	v_max_f32_e32 v73, 0, v73
	v_max_f32_e32 v74, 0, v74
	v_cvt_pk_bf16_f32 v81, v81, v82
	v_cvt_pk_bf16_f32 v82, v88, v85
	v_cvt_pk_bf16_f32 v83, v86, v83
	global_store_dwordx4 v[92:93], v[80:83], off offset:256 nt
	v_max_f32_e32 v76, 0, v76
	v_mul_f32_e32 v76, v76, v76
	v_mul_f32_e32 v80, v72, v72
	v_max_f32_e32 v72, 0, v77
	v_mul_f32_e32 v77, v73, v73
	v_max_f32_e32 v73, 0, v78
	v_mul_f32_e32 v78, v74, v74
	v_max_f32_e32 v74, 0, v79
	v_mul_f32_e32 v72, v72, v72
	v_mul_f32_e32 v73, v73, v73
	v_mul_f32_e32 v74, v74, v74
	v_cvt_pk_bf16_f32 v72, v76, v72
	v_cvt_pk_bf16_f32 v73, v73, v74
	v_cvt_pk_bf16_f32 v74, v80, v77
	v_lshlrev_b64 v[76:77], 13, v[146:147]
	v_lshl_add_u64 v[76:77], s[6:7], 0, v[76:77]
	v_max_f32_e32 v75, 0, v75
	v_lshl_add_u64 v[76:77], v[76:77], 0, s[2:3]
	v_pk_mul_f32 v[64:65], v[64:65], v[162:163] op_sel_hi:[1,0]
	v_mul_f32_e32 v75, v75, v75
	v_lshl_add_u64 v[76:77], v[76:77], 0, v[136:137]
	v_pk_mul_f32 v[68:69], v[68:69], v[162:163] op_sel_hi:[1,0]
	v_pk_mul_f32 v[66:67], v[66:67], v[162:163] op_sel_hi:[1,0]
	v_max_f32_e32 v64, 0, v64
	v_cvt_pk_bf16_f32 v75, v78, v75
	global_store_dwordx4 v[76:77], v[72:75], off nt
	v_pk_mul_f32 v[70:71], v[70:71], v[162:163] op_sel_hi:[1,0]
	v_max_f32_e32 v65, 0, v65
	v_mul_f32_e32 v72, v64, v64
	v_max_f32_e32 v64, 0, v69
	v_max_f32_e32 v66, 0, v66
	v_max_f32_e32 v68, 0, v68
	v_mul_f32_e32 v64, v64, v64
	v_mul_f32_e32 v69, v65, v65
	v_max_f32_e32 v65, 0, v70
	v_mul_f32_e32 v70, v66, v66
	v_max_f32_e32 v66, 0, v71
	v_max_f32_e32 v67, 0, v67
	v_pk_mul_f32 v[58:59], v[58:59], v[158:159] op_sel_hi:[1,0]
	v_pk_mul_f32 v[56:57], v[56:57], v[158:159] op_sel_hi:[1,0]
	v_mul_f32_e32 v68, v68, v68
	v_mul_f32_e32 v65, v65, v65
	v_mul_f32_e32 v66, v66, v66
	v_mul_f32_e32 v67, v67, v67
	v_cvt_pk_bf16_f32 v64, v68, v64
	v_pk_mul_f32 v[62:63], v[62:63], v[158:159] op_sel_hi:[1,0]
	v_pk_mul_f32 v[60:61], v[60:61], v[158:159] op_sel_hi:[1,0]
	v_max_f32_e32 v56, 0, v56
	v_max_f32_e32 v57, 0, v57
	v_max_f32_e32 v58, 0, v58
	v_cvt_pk_bf16_f32 v65, v65, v66
	v_cvt_pk_bf16_f32 v66, v72, v69
	v_cvt_pk_bf16_f32 v67, v70, v67
	global_store_dwordx4 v[76:77], v[64:67], off offset:256 nt
	v_max_f32_e32 v59, 0, v59
	v_max_f32_e32 v60, 0, v60
	v_mul_f32_e32 v64, v56, v56
	v_max_f32_e32 v56, 0, v61
	v_mul_f32_e32 v61, v57, v57
	v_max_f32_e32 v57, 0, v62
	v_mul_f32_e32 v62, v58, v58
	v_max_f32_e32 v58, 0, v63
	v_mul_f32_e32 v56, v56, v56
	v_mul_f32_e32 v57, v57, v57
	v_mul_f32_e32 v58, v58, v58
	v_mul_f32_e32 v59, v59, v59
	v_mul_f32_e32 v60, v60, v60
	v_cvt_pk_bf16_f32 v56, v60, v56
	v_cvt_pk_bf16_f32 v57, v57, v58
	v_cvt_pk_bf16_f32 v58, v64, v61
	v_cvt_pk_bf16_f32 v59, v62, v59
	v_add_co_u32_e32 v62, vcc, s55, v120
	v_pk_mul_f32 v[48:49], v[48:49], v[158:159] op_sel_hi:[1,0]
	s_nop 0
	v_addc_co_u32_e32 v63, vcc, 0, v121, vcc
	v_pk_mul_f32 v[52:53], v[52:53], v[158:159] op_sel_hi:[1,0]
	v_pk_mul_f32 v[50:51], v[50:51], v[158:159] op_sel_hi:[1,0]
	v_max_f32_e32 v48, 0, v48
	global_store_dwordx4 v[62:63], v[56:59], off nt
	v_pk_mul_f32 v[54:55], v[54:55], v[158:159] op_sel_hi:[1,0]
	v_max_f32_e32 v49, 0, v49
	v_mul_f32_e32 v56, v48, v48
	v_max_f32_e32 v48, 0, v53
	v_max_f32_e32 v50, 0, v50
	v_max_f32_e32 v52, 0, v52
	v_mul_f32_e32 v48, v48, v48
	v_mul_f32_e32 v53, v49, v49
	v_max_f32_e32 v49, 0, v54
	v_mul_f32_e32 v54, v50, v50
	v_max_f32_e32 v50, 0, v55
	v_max_f32_e32 v51, 0, v51
	v_pk_mul_f32 v[42:43], v[42:43], v[156:157] op_sel_hi:[1,0]
	v_pk_mul_f32 v[40:41], v[40:41], v[156:157] op_sel_hi:[1,0]
	v_lshl_add_u64 v[60:61], v[120:121], 0, s[18:19]
	v_mul_f32_e32 v52, v52, v52
	v_mul_f32_e32 v49, v49, v49
	v_mul_f32_e32 v50, v50, v50
	v_mul_f32_e32 v51, v51, v51
	v_cvt_pk_bf16_f32 v48, v52, v48
	v_pk_mul_f32 v[46:47], v[46:47], v[156:157] op_sel_hi:[1,0]
	v_pk_mul_f32 v[44:45], v[44:45], v[156:157] op_sel_hi:[1,0]
	v_max_f32_e32 v40, 0, v40
	v_max_f32_e32 v41, 0, v41
	v_max_f32_e32 v42, 0, v42
	v_cvt_pk_bf16_f32 v49, v49, v50
	v_cvt_pk_bf16_f32 v50, v56, v53
	v_cvt_pk_bf16_f32 v51, v54, v51
	global_store_dwordx4 v[60:61], v[48:51], off offset:256 nt
	v_max_f32_e32 v43, 0, v43
	v_max_f32_e32 v44, 0, v44
	v_mul_f32_e32 v48, v40, v40
	v_max_f32_e32 v40, 0, v45
	v_mul_f32_e32 v45, v41, v41
	v_max_f32_e32 v41, 0, v46
	v_mul_f32_e32 v46, v42, v42
	v_max_f32_e32 v42, 0, v47
	v_mul_f32_e32 v40, v40, v40
	v_mul_f32_e32 v41, v41, v41
	v_mul_f32_e32 v42, v42, v42
	v_mul_f32_e32 v43, v43, v43
	v_mul_f32_e32 v44, v44, v44
	v_cvt_pk_bf16_f32 v40, v44, v40
	v_cvt_pk_bf16_f32 v41, v41, v42
	v_cvt_pk_bf16_f32 v42, v48, v45
	v_cvt_pk_bf16_f32 v43, v46, v43
	v_add_co_u32_e32 v46, vcc, s56, v120
	v_pk_mul_f32 v[32:33], v[32:33], v[156:157] op_sel_hi:[1,0]
	s_nop 0
	v_addc_co_u32_e32 v47, vcc, 0, v121, vcc
	v_pk_mul_f32 v[36:37], v[36:37], v[156:157] op_sel_hi:[1,0]
	v_pk_mul_f32 v[34:35], v[34:35], v[156:157] op_sel_hi:[1,0]
	v_max_f32_e32 v32, 0, v32
	global_store_dwordx4 v[46:47], v[40:43], off nt
	v_pk_mul_f32 v[38:39], v[38:39], v[156:157] op_sel_hi:[1,0]
	v_max_f32_e32 v33, 0, v33
	v_mul_f32_e32 v40, v32, v32
	v_max_f32_e32 v32, 0, v37
	v_max_f32_e32 v34, 0, v34
	v_max_f32_e32 v36, 0, v36
	v_mul_f32_e32 v32, v32, v32
	v_mul_f32_e32 v37, v33, v33
	v_max_f32_e32 v33, 0, v38
	v_mul_f32_e32 v38, v34, v34
	v_max_f32_e32 v34, 0, v39
	v_max_f32_e32 v35, 0, v35
	v_pk_mul_f32 v[26:27], v[26:27], v[154:155] op_sel_hi:[1,0]
	v_pk_mul_f32 v[24:25], v[24:25], v[154:155] op_sel_hi:[1,0]
	v_lshl_add_u64 v[44:45], v[120:121], 0, s[20:21]
	v_mul_f32_e32 v36, v36, v36
	v_mul_f32_e32 v33, v33, v33
	v_mul_f32_e32 v34, v34, v34
	v_mul_f32_e32 v35, v35, v35
	v_cvt_pk_bf16_f32 v32, v36, v32
	v_pk_mul_f32 v[30:31], v[30:31], v[154:155] op_sel_hi:[1,0]
	v_pk_mul_f32 v[28:29], v[28:29], v[154:155] op_sel_hi:[1,0]
	v_max_f32_e32 v24, 0, v24
	v_max_f32_e32 v25, 0, v25
	v_max_f32_e32 v26, 0, v26
	v_cvt_pk_bf16_f32 v33, v33, v34
	v_cvt_pk_bf16_f32 v34, v40, v37
	v_cvt_pk_bf16_f32 v35, v38, v35
	global_store_dwordx4 v[44:45], v[32:35], off offset:256 nt
	v_max_f32_e32 v27, 0, v27
	v_max_f32_e32 v28, 0, v28
	v_mul_f32_e32 v32, v24, v24
	v_max_f32_e32 v24, 0, v29
	v_mul_f32_e32 v29, v25, v25
	v_max_f32_e32 v25, 0, v30
	v_mul_f32_e32 v30, v26, v26
	v_max_f32_e32 v26, 0, v31
	v_mul_f32_e32 v24, v24, v24
	v_mul_f32_e32 v25, v25, v25
	v_mul_f32_e32 v26, v26, v26
	v_mul_f32_e32 v27, v27, v27
	v_mul_f32_e32 v28, v28, v28
	v_cvt_pk_bf16_f32 v24, v28, v24
	v_cvt_pk_bf16_f32 v25, v25, v26
	v_cvt_pk_bf16_f32 v26, v32, v29
	v_cvt_pk_bf16_f32 v27, v30, v27
	v_add_co_u32_e32 v30, vcc, s57, v120
	v_pk_mul_f32 v[16:17], v[16:17], v[154:155] op_sel_hi:[1,0]
	s_nop 0
	v_addc_co_u32_e32 v31, vcc, 0, v121, vcc
	v_pk_mul_f32 v[20:21], v[20:21], v[154:155] op_sel_hi:[1,0]
	v_pk_mul_f32 v[18:19], v[18:19], v[154:155] op_sel_hi:[1,0]
	v_max_f32_e32 v16, 0, v16
	global_store_dwordx4 v[30:31], v[24:27], off nt
	v_pk_mul_f32 v[22:23], v[22:23], v[154:155] op_sel_hi:[1,0]
	v_max_f32_e32 v17, 0, v17
	v_mul_f32_e32 v24, v16, v16
	v_max_f32_e32 v16, 0, v21
	v_max_f32_e32 v18, 0, v18
	v_max_f32_e32 v20, 0, v20
	v_mul_f32_e32 v16, v16, v16
	v_mul_f32_e32 v21, v17, v17
	v_max_f32_e32 v17, 0, v22
	v_mul_f32_e32 v22, v18, v18
	v_max_f32_e32 v18, 0, v23
	v_max_f32_e32 v19, 0, v19
	v_pk_mul_f32 v[10:11], v[10:11], v[150:151] op_sel_hi:[1,0]
	v_pk_mul_f32 v[8:9], v[8:9], v[150:151] op_sel_hi:[1,0]
	v_lshl_add_u64 v[28:29], v[120:121], 0, s[22:23]
	v_mul_f32_e32 v20, v20, v20
	v_mul_f32_e32 v17, v17, v17
	v_mul_f32_e32 v18, v18, v18
	v_mul_f32_e32 v19, v19, v19
	v_cvt_pk_bf16_f32 v16, v20, v16
	v_pk_mul_f32 v[14:15], v[14:15], v[150:151] op_sel_hi:[1,0]
	v_pk_mul_f32 v[12:13], v[12:13], v[150:151] op_sel_hi:[1,0]
	v_max_f32_e32 v8, 0, v8
	v_max_f32_e32 v9, 0, v9
	v_max_f32_e32 v10, 0, v10
	v_cvt_pk_bf16_f32 v17, v17, v18
	v_cvt_pk_bf16_f32 v18, v24, v21
	v_cvt_pk_bf16_f32 v19, v22, v19
	global_store_dwordx4 v[28:29], v[16:19], off offset:256 nt
	v_max_f32_e32 v11, 0, v11
	v_max_f32_e32 v12, 0, v12
	v_mul_f32_e32 v16, v8, v8
	v_max_f32_e32 v8, 0, v13
	v_mul_f32_e32 v13, v9, v9
	v_max_f32_e32 v9, 0, v14
	v_mul_f32_e32 v14, v10, v10
	v_max_f32_e32 v10, 0, v15
	v_mul_f32_e32 v8, v8, v8
	v_mul_f32_e32 v9, v9, v9
	v_mul_f32_e32 v10, v10, v10
	v_mul_f32_e32 v11, v11, v11
	v_mul_f32_e32 v12, v12, v12
	v_cvt_pk_bf16_f32 v8, v12, v8
	v_cvt_pk_bf16_f32 v9, v9, v10
	v_cvt_pk_bf16_f32 v10, v16, v13
	v_cvt_pk_bf16_f32 v11, v14, v11
	v_add_co_u32_e32 v14, vcc, s58, v120
	v_pk_mul_f32 v[2:3], v[2:3], v[150:151] op_sel_hi:[1,0]
	v_pk_mul_f32 v[0:1], v[0:1], v[150:151] op_sel_hi:[1,0]
	v_addc_co_u32_e32 v15, vcc, 0, v121, vcc
	v_pk_mul_f32 v[6:7], v[6:7], v[150:151] op_sel_hi:[1,0]
	v_pk_mul_f32 v[4:5], v[4:5], v[150:151] op_sel_hi:[1,0]
	v_max_f32_e32 v0, 0, v0
	v_max_f32_e32 v1, 0, v1
	v_max_f32_e32 v2, 0, v2
	global_store_dwordx4 v[14:15], v[8:11], off nt
	v_max_f32_e32 v3, 0, v3
	v_lshl_add_u64 v[12:13], v[120:121], 0, s[24:25]
	v_mul_f32_e32 v8, v0, v0
	v_max_f32_e32 v0, 0, v5
	v_mul_f32_e32 v5, v1, v1
	v_max_f32_e32 v1, 0, v6
	v_mul_f32_e32 v6, v2, v2
	v_max_f32_e32 v2, 0, v7
	v_max_f32_e32 v4, 0, v4
	v_mul_f32_e32 v0, v0, v0
	v_mul_f32_e32 v1, v1, v1
	v_mul_f32_e32 v2, v2, v2
	v_mul_f32_e32 v3, v3, v3
	s_andn2_b64 vcc, exec, s[0:1]
	s_mov_b64 s[0:1], -1
	v_mul_f32_e32 v4, v4, v4
	v_cvt_pk_bf16_f32 v0, v4, v0
	v_cvt_pk_bf16_f32 v1, v1, v2
	v_cvt_pk_bf16_f32 v2, v8, v5
	v_cvt_pk_bf16_f32 v3, v6, v3
	global_store_dwordx4 v[12:13], v[0:3], off offset:256 nt
	s_cbranch_vccnz .LBB0_2105
	s_andn2_b64 vcc, exec, s[10:11]
	s_cbranch_vccnz .LBB0_2104
	s_barrier
	s_branch .LBB0_2104

.LBB0_2183:
	s_lshl_b32 s20, s19, 8
	v_lshl_add_u32 v168, s18, 8, v155
	s_ashr_i32 s21, s20, 31
	s_lshl_b64 s[18:19], s[20:21], 1
	v_ashrrev_i32_e32 v169, 31, v168
	v_lshl_add_u64 v[128:129], v[156:157], 0, s[18:19]
	v_lshlrev_b64 v[130:131], 11, v[168:169]
	v_lshl_add_u64 v[130:131], v[128:129], 0, v[130:131]
	global_load_dwordx4 v[140:143], v[130:131], off
	global_load_dwordx4 v[136:139], v[130:131], off offset:256
	v_or_b32_e32 v174, 16, v168
	v_ashrrev_i32_e32 v175, 31, v174
	v_lshlrev_b64 v[130:131], 11, v[174:175]
	v_lshl_add_u64 v[128:129], v[128:129], 0, v[130:131]
	global_load_dwordx4 v[132:135], v[128:129], off
	s_nop 0
	global_load_dwordx4 v[128:131], v[128:129], off offset:256
	v_or_b32_e32 v176, 32, v168
	v_ashrrev_i32_e32 v177, 31, v176
	v_readlane_b32 s44, v244, 0
	v_or_b32_e32 v178, 48, v168
	v_lshlrev_b64 v[186:187], 11, v[176:177]
	v_readlane_b32 s45, v244, 1
	v_readlane_b32 s46, v244, 2
	v_readlane_b32 s47, v244, 3
	v_readlane_b32 s48, v244, 4
	v_readlane_b32 s49, v244, 5
	v_lshlrev_b64 v[184:185], 12, v[168:169]
	v_ashrrev_i32_e32 v179, 31, v178
	v_readlane_b32 s50, v244, 6
	v_readlane_b32 s51, v244, 7
	s_mov_b64 s[44:45], s[48:49]
	v_lshl_add_u64 v[186:187], s[4:5], 0, v[186:187]
	v_lshlrev_b32_e32 v152, 1, v154
	s_lshl_b64 s[20:21], s[20:21], 2
	v_lshl_add_u64 v[184:185], s[44:45], 0, v[184:185]
	v_lshlrev_b64 v[188:189], 11, v[178:179]
	v_lshl_add_u64 v[186:187], v[186:187], 0, s[18:19]
	v_lshlrev_b32_e32 v166, 2, v154
	v_mov_b32_e32 v167, v153
	v_add_u32_e32 v172, 0x80, v168
	v_lshl_add_u64 v[184:185], v[184:185], 0, s[20:21]
	v_lshl_add_u64 v[188:189], s[4:5], 0, v[188:189]
	v_lshl_add_u64 v[190:191], v[186:187], 0, v[152:153]
	v_ashrrev_i32_e32 v173, 31, v172
	v_lshl_add_u64 v[194:195], v[184:185], 0, v[166:167]
	v_lshl_add_u64 v[188:189], v[188:189], 0, s[18:19]
	global_load_dwordx4 v[184:187], v[190:191], off
	v_lshlrev_b64 v[174:175], 12, v[174:175]
	v_lshlrev_b64 v[192:193], 11, v[172:173]
	v_lshl_add_u64 v[196:197], v[188:189], 0, v[152:153]
	global_load_dwordx4 v[188:191], v[190:191], off offset:256
	v_add_u32_e32 v170, 0x90, v168
	v_ashrrev_i32_e32 v171, 31, v170
	s_andn2_b64 vcc, exec, s[0:1]
	s_mov_b64 s[0:1], -1
	s_mov_b64 s[46:47], s[50:51]
	s_waitcnt vmcnt(0)
	v_lshlrev_b32_e32 v198, 16, v140
	v_and_b32_e32 v199, 0xffff0000, v140
	v_lshlrev_b32_e32 v140, 16, v141
	v_and_b32_e32 v141, 0xffff0000, v141
	v_lshlrev_b32_e32 v200, 16, v142
	v_and_b32_e32 v201, 0xffff0000, v142
	v_lshlrev_b32_e32 v142, 16, v143
	v_and_b32_e32 v143, 0xffff0000, v143
	v_lshlrev_b32_e32 v202, 16, v136
	v_and_b32_e32 v203, 0xffff0000, v136
	v_lshlrev_b32_e32 v136, 16, v137
	v_and_b32_e32 v137, 0xffff0000, v137
	v_lshlrev_b32_e32 v204, 16, v138
	v_and_b32_e32 v205, 0xffff0000, v138
	v_lshlrev_b32_e32 v138, 16, v139
	v_and_b32_e32 v139, 0xffff0000, v139
	v_pk_add_f32 v[124:125], v[124:125], v[198:199]
	v_pk_add_f32 v[126:127], v[126:127], v[140:141]
	v_pk_add_f32 v[120:121], v[120:121], v[200:201]
	v_pk_add_f32 v[122:123], v[122:123], v[142:143]
	v_pk_add_f32 v[116:117], v[116:117], v[202:203]
	v_pk_add_f32 v[118:119], v[118:119], v[136:137]
	v_pk_add_f32 v[112:113], v[112:113], v[204:205]
	v_pk_add_f32 v[114:115], v[114:115], v[138:139]
	global_store_dwordx4 v[194:195], v[124:127], off nt
	global_store_dwordx4 v[194:195], v[120:123], off offset:16 nt
	global_store_dwordx4 v[194:195], v[116:119], off offset:512 nt
	global_store_dwordx4 v[194:195], v[112:115], off offset:528 nt
	global_load_dwordx4 v[112:115], v[196:197], off
	v_lshl_add_u64 v[116:117], s[44:45], 0, v[174:175]
	v_lshl_add_u64 v[118:119], s[4:5], 0, v[192:193]
	v_lshl_add_u64 v[116:117], v[116:117], 0, s[20:21]
	v_lshl_add_u64 v[118:119], v[118:119], 0, s[18:19]
	v_lshl_add_u64 v[122:123], v[116:117], 0, v[166:167]
	v_lshl_add_u64 v[124:125], v[118:119], 0, v[152:153]
	global_load_dwordx4 v[116:119], v[196:197], off offset:256
	v_lshlrev_b32_e32 v126, 16, v132
	v_and_b32_e32 v127, 0xffff0000, v132
	v_lshlrev_b32_e32 v132, 16, v133
	v_and_b32_e32 v133, 0xffff0000, v133
	v_lshlrev_b32_e32 v136, 16, v134
	v_and_b32_e32 v137, 0xffff0000, v134
	v_lshlrev_b32_e32 v134, 16, v135
	v_and_b32_e32 v135, 0xffff0000, v135
	v_lshlrev_b32_e32 v138, 16, v128
	v_and_b32_e32 v139, 0xffff0000, v128
	v_lshlrev_b32_e32 v128, 16, v129
	v_and_b32_e32 v129, 0xffff0000, v129
	v_lshlrev_b32_e32 v140, 16, v130
	v_and_b32_e32 v141, 0xffff0000, v130
	v_lshlrev_b32_e32 v130, 16, v131
	v_and_b32_e32 v131, 0xffff0000, v131
	v_pk_add_f32 v[108:109], v[108:109], v[126:127]
	v_pk_add_f32 v[110:111], v[110:111], v[132:133]
	v_pk_add_f32 v[104:105], v[104:105], v[136:137]
	v_pk_add_f32 v[106:107], v[106:107], v[134:135]
	v_pk_add_f32 v[100:101], v[100:101], v[138:139]
	v_pk_add_f32 v[102:103], v[102:103], v[128:129]
	v_pk_add_f32 v[96:97], v[96:97], v[140:141]
	v_pk_add_f32 v[98:99], v[98:99], v[130:131]
	global_store_dwordx4 v[122:123], v[108:111], off nt
	global_store_dwordx4 v[122:123], v[104:107], off offset:16 nt
	global_store_dwordx4 v[122:123], v[100:103], off offset:512 nt
	global_store_dwordx4 v[122:123], v[96:99], off offset:528 nt
	global_load_dwordx4 v[96:99], v[124:125], off
	v_lshlrev_b64 v[100:101], 11, v[170:171]
	v_lshlrev_b64 v[102:103], 12, v[178:179]
	v_lshl_add_u64 v[100:101], s[4:5], 0, v[100:101]
	v_lshl_add_u64 v[102:103], s[44:45], 0, v[102:103]
	v_lshl_add_u64 v[100:101], v[100:101], 0, s[18:19]
	v_lshl_add_u64 v[102:103], v[102:103], 0, s[20:21]
	v_lshl_add_u64 v[106:107], v[100:101], 0, v[152:153]
	v_lshl_add_u64 v[108:109], v[102:103], 0, v[166:167]
	global_load_dwordx4 v[100:103], v[124:125], off offset:256
	v_lshlrev_b64 v[120:121], 12, v[176:177]
	v_lshl_add_u64 v[104:105], s[44:45], 0, v[120:121]
	v_lshl_add_u64 v[104:105], v[104:105], 0, s[20:21]
	v_lshlrev_b32_e32 v110, 16, v184
	v_and_b32_e32 v111, 0xffff0000, v184
	v_lshlrev_b32_e32 v120, 16, v185
	v_and_b32_e32 v121, 0xffff0000, v185
	v_lshlrev_b32_e32 v122, 16, v186
	v_and_b32_e32 v123, 0xffff0000, v186
	v_lshlrev_b32_e32 v124, 16, v187
	v_and_b32_e32 v125, 0xffff0000, v187
	v_lshl_add_u64 v[104:105], v[104:105], 0, v[166:167]
	v_lshlrev_b32_e32 v126, 16, v188
	v_and_b32_e32 v127, 0xffff0000, v188
	v_lshlrev_b32_e32 v128, 16, v189
	v_and_b32_e32 v129, 0xffff0000, v189
	v_lshlrev_b32_e32 v130, 16, v190
	v_and_b32_e32 v131, 0xffff0000, v190
	v_lshlrev_b32_e32 v132, 16, v191
	v_and_b32_e32 v133, 0xffff0000, v191
	v_pk_add_f32 v[92:93], v[92:93], v[110:111]
	v_pk_add_f32 v[94:95], v[94:95], v[120:121]
	v_pk_add_f32 v[88:89], v[88:89], v[122:123]
	v_pk_add_f32 v[90:91], v[90:91], v[124:125]
	v_pk_add_f32 v[84:85], v[84:85], v[126:127]
	v_pk_add_f32 v[86:87], v[86:87], v[128:129]
	v_pk_add_f32 v[80:81], v[80:81], v[130:131]
	v_pk_add_f32 v[82:83], v[82:83], v[132:133]
	global_store_dwordx4 v[104:105], v[92:95], off nt
	global_store_dwordx4 v[104:105], v[88:91], off offset:16 nt
	global_store_dwordx4 v[104:105], v[84:87], off offset:512 nt
	global_store_dwordx4 v[104:105], v[80:83], off offset:528 nt
	global_load_dwordx4 v[80:83], v[106:107], off
	s_nop 0
	global_load_dwordx4 v[84:87], v[106:107], off offset:256
	s_waitcnt vmcnt(13)
	v_lshlrev_b32_e32 v88, 16, v112
	v_and_b32_e32 v89, 0xffff0000, v112
	v_lshlrev_b32_e32 v90, 16, v113
	v_and_b32_e32 v91, 0xffff0000, v113
	v_lshlrev_b32_e32 v92, 16, v114
	v_and_b32_e32 v93, 0xffff0000, v114
	v_lshlrev_b32_e32 v94, 16, v115
	v_and_b32_e32 v95, 0xffff0000, v115
	v_pk_add_f32 v[76:77], v[76:77], v[88:89]
	v_pk_add_f32 v[78:79], v[78:79], v[90:91]
	v_pk_add_f32 v[72:73], v[72:73], v[92:93]
	v_pk_add_f32 v[74:75], v[74:75], v[94:95]
	global_store_dwordx4 v[108:109], v[76:79], off nt
	global_store_dwordx4 v[108:109], v[72:75], off offset:16 nt
	s_waitcnt vmcnt(14)
	v_lshlrev_b32_e32 v104, 16, v116
	v_and_b32_e32 v105, 0xffff0000, v116
	v_lshlrev_b32_e32 v72, 16, v118
	v_and_b32_e32 v73, 0xffff0000, v118
	v_pk_add_f32 v[64:65], v[64:65], v[72:73]
	v_lshlrev_b32_e32 v72, 16, v119
	v_and_b32_e32 v73, 0xffff0000, v119
	v_lshlrev_b32_e32 v106, 16, v117
	v_and_b32_e32 v107, 0xffff0000, v117
	v_pk_add_f32 v[66:67], v[66:67], v[72:73]
	v_add_u32_e32 v72, 0xa0, v168
	v_pk_add_f32 v[68:69], v[68:69], v[104:105]
	v_pk_add_f32 v[70:71], v[70:71], v[106:107]
	v_ashrrev_i32_e32 v73, 31, v72
	global_store_dwordx4 v[108:109], v[68:71], off offset:512 nt
	global_store_dwordx4 v[108:109], v[64:67], off offset:528 nt
	v_lshlrev_b64 v[74:75], 12, v[172:173]
	v_lshl_add_u64 v[74:75], s[44:45], 0, v[74:75]
	v_lshlrev_b64 v[64:65], 11, v[72:73]
	v_lshl_add_u64 v[64:65], s[4:5], 0, v[64:65]
	v_lshl_add_u64 v[64:65], v[64:65], 0, s[18:19]
	s_waitcnt vmcnt(11)
	v_lshlrev_b32_e32 v76, 16, v96
	v_and_b32_e32 v77, 0xffff0000, v96
	v_pk_add_f32 v[60:61], v[60:61], v[76:77]
	v_lshlrev_b32_e32 v76, 16, v97
	v_and_b32_e32 v77, 0xffff0000, v97
	v_pk_add_f32 v[62:63], v[62:63], v[76:77]
	v_lshlrev_b32_e32 v76, 16, v98
	v_and_b32_e32 v77, 0xffff0000, v98
	v_lshl_add_u64 v[74:75], v[74:75], 0, s[20:21]
	v_lshl_add_u64 v[68:69], v[64:65], 0, v[152:153]
	v_pk_add_f32 v[56:57], v[56:57], v[76:77]
	v_lshlrev_b32_e32 v76, 16, v99
	v_and_b32_e32 v77, 0xffff0000, v99
	v_lshl_add_u64 v[74:75], v[74:75], 0, v[166:167]
	global_load_dwordx4 v[64:67], v[68:69], off
	s_nop 0
	global_load_dwordx4 v[68:71], v[68:69], off offset:256
	v_pk_add_f32 v[58:59], v[58:59], v[76:77]
	global_store_dwordx4 v[74:75], v[60:63], off nt
	global_store_dwordx4 v[74:75], v[56:59], off offset:16 nt
	s_waitcnt vmcnt(9)
	v_lshlrev_b32_e32 v60, 16, v80
	v_lshlrev_b32_e32 v56, 16, v100
	v_and_b32_e32 v57, 0xffff0000, v100
	v_pk_add_f32 v[52:53], v[52:53], v[56:57]
	v_lshlrev_b32_e32 v56, 16, v101
	v_and_b32_e32 v57, 0xffff0000, v101
	v_pk_add_f32 v[54:55], v[54:55], v[56:57]
	v_lshlrev_b32_e32 v56, 16, v102
	v_and_b32_e32 v57, 0xffff0000, v102
	v_pk_add_f32 v[48:49], v[48:49], v[56:57]
	v_lshlrev_b32_e32 v56, 16, v103
	v_and_b32_e32 v57, 0xffff0000, v103
	v_pk_add_f32 v[50:51], v[50:51], v[56:57]
	v_add_u32_e32 v56, 0xb0, v168
	v_ashrrev_i32_e32 v57, 31, v56
	global_store_dwordx4 v[74:75], v[52:55], off offset:512 nt
	global_store_dwordx4 v[74:75], v[48:51], off offset:528 nt
	v_and_b32_e32 v61, 0xffff0000, v80
	v_pk_add_f32 v[44:45], v[44:45], v[60:61]
	v_lshlrev_b64 v[48:49], 11, v[56:57]
	v_lshl_add_u64 v[48:49], s[4:5], 0, v[48:49]
	v_lshl_add_u64 v[48:49], v[48:49], 0, s[18:19]
	v_lshl_add_u64 v[58:59], v[48:49], 0, v[152:153]
	global_load_dwordx4 v[48:51], v[58:59], off
	global_load_dwordx4 v[52:55], v[58:59], off offset:256
	v_lshlrev_b64 v[58:59], 12, v[170:171]
	v_lshlrev_b32_e32 v60, 16, v81
	v_and_b32_e32 v61, 0xffff0000, v81
	v_lshl_add_u64 v[58:59], s[44:45], 0, v[58:59]
	v_pk_add_f32 v[46:47], v[46:47], v[60:61]
	v_lshlrev_b32_e32 v60, 16, v82
	v_and_b32_e32 v61, 0xffff0000, v82
	v_lshl_add_u64 v[58:59], v[58:59], 0, s[20:21]
	v_pk_add_f32 v[40:41], v[40:41], v[60:61]
	v_lshlrev_b32_e32 v60, 16, v83
	v_and_b32_e32 v61, 0xffff0000, v83
	v_lshl_add_u64 v[58:59], v[58:59], 0, v[166:167]
	v_pk_add_f32 v[42:43], v[42:43], v[60:61]
	global_store_dwordx4 v[58:59], v[44:47], off nt
	global_store_dwordx4 v[58:59], v[40:43], off offset:16 nt
	s_waitcnt vmcnt(14)
	s_nop 0
	v_lshlrev_b32_e32 v40, 16, v84
	v_and_b32_e32 v41, 0xffff0000, v84
	v_pk_add_f32 v[36:37], v[36:37], v[40:41]
	v_lshlrev_b32_e32 v40, 16, v85
	v_and_b32_e32 v41, 0xffff0000, v85
	v_pk_add_f32 v[38:39], v[38:39], v[40:41]
	v_lshlrev_b32_e32 v40, 16, v86
	v_and_b32_e32 v41, 0xffff0000, v86
	v_pk_add_f32 v[28:29], v[28:29], v[40:41]
	v_lshlrev_b32_e32 v40, 16, v87
	v_and_b32_e32 v41, 0xffff0000, v87
	v_pk_add_f32 v[30:31], v[30:31], v[40:41]
	global_store_dwordx4 v[58:59], v[36:39], off offset:512 nt
	global_store_dwordx4 v[58:59], v[28:31], off offset:528 nt
	s_nop 0
	v_lshlrev_b64 v[36:37], 12, v[72:73]
	s_waitcnt vmcnt(11)
	v_lshlrev_b32_e32 v28, 16, v64
	v_and_b32_e32 v29, 0xffff0000, v64
	v_pk_add_f32 v[28:29], v[32:33], v[28:29]
	v_lshlrev_b32_e32 v32, 16, v66
	v_and_b32_e32 v33, 0xffff0000, v66
	v_pk_add_f32 v[24:25], v[24:25], v[32:33]
	v_lshlrev_b32_e32 v32, 16, v67
	v_and_b32_e32 v33, 0xffff0000, v67
	v_pk_add_f32 v[26:27], v[26:27], v[32:33]
	v_lshl_add_u64 v[32:33], s[44:45], 0, v[36:37]
	v_lshlrev_b32_e32 v30, 16, v65
	v_and_b32_e32 v31, 0xffff0000, v65
	v_lshl_add_u64 v[32:33], v[32:33], 0, s[20:21]
	v_pk_add_f32 v[30:31], v[34:35], v[30:31]
	v_lshl_add_u64 v[32:33], v[32:33], 0, v[166:167]
	global_store_dwordx4 v[32:33], v[28:31], off nt
	global_store_dwordx4 v[32:33], v[24:27], off offset:16 nt
	s_waitcnt vmcnt(12)
	s_nop 0
	v_lshlrev_b32_e32 v24, 16, v68
	v_and_b32_e32 v25, 0xffff0000, v68
	v_pk_add_f32 v[20:21], v[20:21], v[24:25]
	v_lshlrev_b32_e32 v24, 16, v69
	v_and_b32_e32 v25, 0xffff0000, v69
	v_pk_add_f32 v[22:23], v[22:23], v[24:25]
	v_lshlrev_b32_e32 v24, 16, v70
	v_and_b32_e32 v25, 0xffff0000, v70
	v_pk_add_f32 v[12:13], v[12:13], v[24:25]
	v_lshlrev_b32_e32 v24, 16, v71
	v_and_b32_e32 v25, 0xffff0000, v71
	v_pk_add_f32 v[14:15], v[14:15], v[24:25]
	global_store_dwordx4 v[32:33], v[20:23], off offset:512 nt
	global_store_dwordx4 v[32:33], v[12:15], off offset:528 nt
	s_nop 0
	v_lshlrev_b64 v[20:21], 12, v[56:57]
	s_waitcnt vmcnt(9)
	v_lshlrev_b32_e32 v12, 16, v48
	v_and_b32_e32 v13, 0xffff0000, v48
	v_pk_add_f32 v[12:13], v[16:17], v[12:13]
	v_lshlrev_b32_e32 v16, 16, v50
	v_and_b32_e32 v17, 0xffff0000, v50
	v_pk_add_f32 v[8:9], v[8:9], v[16:17]
	v_lshlrev_b32_e32 v16, 16, v51
	v_and_b32_e32 v17, 0xffff0000, v51
	v_pk_add_f32 v[10:11], v[10:11], v[16:17]
	v_lshl_add_u64 v[16:17], s[44:45], 0, v[20:21]
	v_lshlrev_b32_e32 v14, 16, v49
	v_and_b32_e32 v15, 0xffff0000, v49
	v_lshl_add_u64 v[16:17], v[16:17], 0, s[20:21]
	v_pk_add_f32 v[14:15], v[18:19], v[14:15]
	v_lshl_add_u64 v[16:17], v[16:17], 0, v[166:167]
	global_store_dwordx4 v[16:17], v[12:15], off nt
	global_store_dwordx4 v[16:17], v[8:11], off offset:16 nt
	s_waitcnt vmcnt(10)
	s_nop 0
	v_lshlrev_b32_e32 v8, 16, v52
	v_and_b32_e32 v9, 0xffff0000, v52
	v_pk_add_f32 v[4:5], v[4:5], v[8:9]
	v_lshlrev_b32_e32 v8, 16, v53
	v_and_b32_e32 v9, 0xffff0000, v53
	v_pk_add_f32 v[6:7], v[6:7], v[8:9]
	v_lshlrev_b32_e32 v8, 16, v54
	v_and_b32_e32 v9, 0xffff0000, v54
	v_pk_add_f32 v[0:1], v[0:1], v[8:9]
	v_lshlrev_b32_e32 v8, 16, v55
	v_and_b32_e32 v9, 0xffff0000, v55
	v_pk_add_f32 v[2:3], v[2:3], v[8:9]
	global_store_dwordx4 v[16:17], v[4:7], off offset:512 nt
	global_store_dwordx4 v[16:17], v[0:3], off offset:528 nt
	s_cbranch_vccnz .LBB0_2176
	s_andn2_b64 vcc, exec, s[2:3]
	s_cbranch_vccnz .LBB0_2175
	s_barrier
	s_branch .LBB0_2175
